# NSA selected-block loop software-pipelined like the diff loop: softmax segment vs PV+QK matrix segment alternate between wave halves, triple-buffered LDS tiles
# speedup vs baseline: 1.0233x; 1.0233x over previous
;     ...
;     if (probe != 1) { kv_gload<DV, HAS_V>(st, Kb, VTb, ldv, jn * 64); kv_sstore<DV, HAS_V>(st, lds); }
;     __syncthreads();
;     ...
;     const u64 mysel = SEL[32 * hq + r];
;     const u64 U = ((UN[0] | UN[1]) | (UN[2] | UN[3])) | ((UN[4] | UN[5]) | (UN[6] | UN[7]));
;     {
;         const bf16_t* Ks = (const bf16_t*)(p.ws + OFF_KS) + (size_t)bg * 4096 * 64;
;         const bf16_t* VsT = (const bf16_t*)(p.ws + OFF_VST) + (size_t)bg * 64 * 4096;
;         const int nts = __popcll(U), j0 = __ffsll((long long)U) - 1;
;         f32x16 o[2];
; #pragma unroll
;         for (int dt = 0; dt < 2; ++dt)
; #pragma unroll
;             for (int i = 0; i < 16; ++i) o[dt][i] = 0.f;
;         float m = -1e30f; f32x16 lv;
; #pragma unroll
;         for (int i = 0; i < 16; ++i) lv[i] = 0.f;
;         kv_loop<64, true>(lds, Ks, VsT, 4096, nts, j0, [U](int j) { return __ffsll((long long)(U & (~0ull << (j + 1)))) - 1; }, [&](int j, const unsigned char* sb) {
.LBB0_538:
	s_or_b64 exec, exec, s[4:5]
	v_readlane_b32 s3, v238, 55
	s_add_i32 s2, 0, 0x19200
	s_waitcnt lgkmcnt(0)
	v_mov_b32_e32 v34, s3
	s_barrier
	ds_read_b128 v[34:37], v34
	v_mov_b32_e32 v38, s2
	ds_read_b128 v[38:41], v38
	v_readlane_b32 s2, v238, 56
	v_readlane_b32 s6, v238, 57
	s_waitcnt lgkmcnt(1)
	v_readfirstlane_b32 s3, v35
	v_mov_b32_e32 v42, s2
	ds_read_b128 v[42:45], v42
	v_readfirstlane_b32 s2, v34
	v_mov_b32_e32 v34, s6
	v_readfirstlane_b32 s5, v37
	v_readfirstlane_b32 s4, v36
	ds_read_b128 v[34:37], v34
	s_waitcnt lgkmcnt(2)
	v_readfirstlane_b32 s15, v39
	v_readfirstlane_b32 s14, v38
	v_readfirstlane_b32 s17, v41
	v_readfirstlane_b32 s16, v40
	s_or_b64 s[14:15], s[16:17], s[14:15]
	s_or_b64 s[2:3], s[14:15], s[2:3]
	s_waitcnt lgkmcnt(1)
	v_readfirstlane_b32 s7, v43
	v_readfirstlane_b32 s6, v42
	s_or_b64 s[2:3], s[2:3], s[4:5]
	v_readfirstlane_b32 s9, v45
	v_readfirstlane_b32 s8, v44
	s_or_b64 s[2:3], s[2:3], s[6:7]
	s_waitcnt lgkmcnt(0)
	v_readfirstlane_b32 s11, v35
	v_readfirstlane_b32 s10, v34
	s_or_b64 s[2:3], s[2:3], s[8:9]
	v_readfirstlane_b32 s13, v37
	v_readfirstlane_b32 s12, v36
	s_or_b64 s[2:3], s[2:3], s[10:11]
	v_lshlrev_b32_e32 v34, 3, v81
	v_lshlrev_b32_e32 v35, 3, v80
	s_or_b64 s[6:7], s[2:3], s[12:13]
	v_readlane_b32 s2, v238, 53
	v_add3_u32 v34, s75, v34, v35
	v_lshlrev_b32_e32 v36, 19, v122
	v_mov_b32_e32 v37, v173
	v_readlane_b32 s3, v238, 54
	s_cmp_eq_u64 s[6:7], 0
	ds_read_b64 v[124:125], v34
	v_lshl_add_u64 v[34:35], s[2:3], 0, v[36:37]
	s_cselect_b64 s[2:3], -1, 0
	s_ff1_i32_b64 s12, s[6:7]
	s_and_b64 vcc, s[2:3], exec
	s_cselect_b32 s2, -1, s12
	v_lshl_add_u32 v38, s2, 6, v187
	v_readlane_b32 s4, v238, 51
	v_ashrrev_i32_e32 v39, 31, v38
	v_readlane_b32 s5, v238, 52
	v_lshlrev_b64 v[38:39], 7, v[38:39]
	s_ashr_i32 s3, s2, 31
	v_lshl_add_u64 v[36:37], s[4:5], 0, v[36:37]
	v_lshl_add_u64 v[38:39], v[34:35], 0, v[38:39]
	s_lshl_b64 s[2:3], s[2:3], 13
	v_lshl_add_u64 v[38:39], v[38:39], 0, v[172:173]
	v_lshl_add_u64 v[40:41], v[36:37], 0, s[2:3]
	v_mov_b32_e32 v175, v173
	v_lshl_add_u64 v[40:41], v[40:41], 0, v[174:175]
	global_load_dwordx4 v[114:117], v[38:39], off
	global_load_dwordx4 v[118:121], v[40:41], off
	s_waitcnt vmcnt(1)
	ds_write_b128 v198, v[114:117]
	s_waitcnt vmcnt(0)
	ds_write2_b64 v199, v[118:119], v[120:121] offset0:128 offset1:130
	s_waitcnt lgkmcnt(0)
	s_barrier
	s_cbranch_vccnz .LBB0_556
	v_lshl_add_u64 v[126:127], v[34:35], 0, v[172:173]
	v_and_b32_e32 v34, 0xffffffc0, v203
	v_mov_b32_e32 v48, v173
	v_mov_b32_e32 v49, v173
	v_lshl_add_u64 v[128:129], v[36:37], 0, v[174:175]
	v_sub_u32_e32 v206, v178, v34
	v_mov_b32_e32 v34, v173
	v_mov_b32_e32 v35, v173
	v_mov_b32_e32 v36, v173
	v_mov_b32_e32 v37, v173
	v_mov_b32_e32 v38, v173
	v_mov_b32_e32 v39, v173
	v_mov_b32_e32 v40, v173
	v_mov_b32_e32 v41, v173
	v_mov_b32_e32 v42, v173
	v_mov_b32_e32 v43, v173
	v_mov_b32_e32 v44, v173
	v_mov_b32_e32 v45, v173
	v_mov_b32_e32 v46, v173
	v_mov_b32_e32 v47, v173
	v_mov_b64_e32 v[64:65], v[48:49]
	v_mov_b64_e32 v[80:81], v[48:49]
	s_bcnt1_i32_b64 s2, s[6:7]
	v_ashrrev_i32_e32 v131, 6, v203
	v_or_b32_e32 v132, 32, v181
	v_or_b32_e32 v133, 33, v181
	v_or_b32_e32 v134, 2, v181
	v_or_b32_e32 v135, 34, v181
	v_or_b32_e32 v136, 3, v181
	v_or_b32_e32 v137, 35, v181
	v_or_b32_e32 v138, 8, v181
	v_or_b32_e32 v139, 40, v181
	v_or_b32_e32 v140, 9, v181
	v_or_b32_e32 v141, 41, v181
	v_or_b32_e32 v142, 10, v181
	v_or_b32_e32 v143, 42, v181
	v_or_b32_e32 v144, 11, v181
	v_or_b32_e32 v145, 43, v181
	v_or_b32_e32 v162, 16, v181
	v_or_b32_e32 v163, 48, v181
	v_or_b32_e32 v164, 17, v181
	v_or_b32_e32 v165, 49, v181
	v_or_b32_e32 v166, 18, v181
	v_or_b32_e32 v167, 50, v181
	v_or_b32_e32 v168, 19, v181
	v_or_b32_e32 v169, 51, v181
	v_or_b32_e32 v175, 24, v181
	v_or_b32_e32 v186, 56, v181
	v_or_b32_e32 v188, 25, v181
	v_or_b32_e32 v189, 57, v181
	v_or_b32_e32 v190, 26, v181
	v_or_b32_e32 v191, 58, v181
	v_or_b32_e32 v192, 27, v181
	v_or_b32_e32 v193, 59, v181
	s_mov_b32 s13, 0
	v_mov_b32_e32 v207, 0xf149f2ca
	v_mov_b64_e32 v[62:63], v[46:47]
	v_mov_b64_e32 v[60:61], v[44:45]
	v_mov_b64_e32 v[58:59], v[42:43]
	v_mov_b64_e32 v[56:57], v[40:41]
	v_mov_b64_e32 v[54:55], v[38:39]
	v_mov_b64_e32 v[52:53], v[36:37]
	v_mov_b64_e32 v[50:51], v[34:35]
	v_mov_b64_e32 v[78:79], v[46:47]
	v_mov_b64_e32 v[76:77], v[44:45]
	v_mov_b64_e32 v[74:75], v[42:43]
	v_mov_b64_e32 v[72:73], v[40:41]
	v_mov_b64_e32 v[70:71], v[38:39]
	v_mov_b64_e32 v[68:69], v[36:37]
	v_mov_b64_e32 v[66:67], v[34:35]
	v_readfirstlane_b32 s28, v0
	v_readfirstlane_b32 s21, v131
	s_bfe_u32 s28, s28, 0x10008
	s_mov_b32 s13, 0
	s_mov_b32 s18, 0
	s_movk_i32 s19, 0x4800
	s_mov_b32 s20, 0x9000
	s_mov_b32 s8, s12
	s_mov_b32 s9, s12
	s_mov_b32 s10, s12

;     ...
;             const bool mine = (mysel >> j) & 1ull;
	v_lshrrev_b64 v[168:169], s12, v[124:125]
	v_and_b32_e32 v168, 1, v168
	v_cmp_ne_u32_e64 s[14:15], 0, v168

;     ...
;     for (int i = 0; i < nt; ++i) {
;         const int j = jn;
;         const bool more = (i + 1 < nt);
;         if (more) { jn = next(j); if (probe != 1) kv_gload<DV, HAS_V>(st, Kb, VTb, ldv, jn * 64); }
	s_cmp_lt_u32 s2, 2
	s_cbranch_scc1 .Lns_p1

;     ...
;         kv_loop<64, true>(lds, Ks, VsT, 4096, nts, j0, [U](int j) { return __ffsll((long long)(U & (~0ull << (j + 1)))) - 1; }, [&](int j, const unsigned char* sb) {
	s_add_i32 s22, s12, 1
	s_lshl_b64 s[22:23], -1, s22
	s_and_b64 s[22:23], s[22:23], s[6:7]
	s_ff1_i32_b64 s8, s[22:23]

; template <int DV, bool HAS_V>
; DI void kv_gload(KVStage<DV>& st, const bf16_t* __restrict__ Kb, const bf16_t* __restrict__ VTb, int ldv, int key0) {
;     const int tid = threadIdx.x;
;     st.k[0] = *(const u32x4*)(Kb + (size_t)(key0 + (tid >> 3)) * 64 + (tid & 7) * 8);
;     if (HAS_V) {
; #pragma unroll
;         for (int i = 0; i < DV / 64; ++i) { const int c = tid + 512 * i; st.v[i] = *(const u32x4*)(VTb + (size_t)(key0 >> 6) * (DV * 64) + c * 8); }
;     }
; }
	s_lshl_b32 s24, s8, 6
	v_add_u32_e32 v188, s24, v187
	v_mov_b32_e32 v189, v173
	v_lshlrev_b64 v[188:189], 7, v[188:189]
	v_lshl_add_u64 v[188:189], v[126:127], 0, v[188:189]
	global_load_dwordx4 v[114:117], v[188:189], off
	s_lshl_b32 s24, s8, 13
	s_mov_b32 s25, 0
	v_lshl_add_u64 v[190:191], v[128:129], 0, s[24:25]
	global_load_dwordx4 v[118:121], v[190:191], off

;     ...
;             const bool mine = (mysel >> j) & 1ull;
;             if (__ballot(mine) != 0ull) {
;                 f32x16 s0, s1; attn_scores(sb, qf, r, h, s0, s1);
.Lns_p1:
	s_cmp_eq_u64 s[14:15], 0
	s_cbranch_scc1 .Lns_p2
	v_add3_u32 v144, s18, v204, v180

; #define MFMA(a, b, c) __builtin_amdgcn_mfma_f32_32x32x16_bf16((a), (b), (c), 0, 0, 0)
; DI void attn_scores(const unsigned char* kb, const bf16x8 (&qf)[4], int r, int h, f32x16& s0, f32x16& s1) {
; #pragma unroll
;     for (int i = 0; i < 16; ++i) { s0[i] = 0.f; s1[i] = 0.f; }
; #pragma unroll
;     for (int s = 0; s < 4; ++s) {
;         const bf16x8 k0 = *(const bf16x8*)(kb + r * KP + s * 32 + h * 16);
;         const bf16x8 k1 = *(const bf16x8*)(kb + (32 + r) * KP + s * 32 + h * 16);
;         s0 = MFMA(k0, qf[s], s0); s1 = MFMA(k1, qf[s], s1);
;     }
; }
	ds_read_b128 v[224:227], v144 offset:0
	ds_read_b128 v[228:231], v144 offset:4608
	ds_read_b128 v[232:235], v144 offset:32
	ds_read_b128 v[132:135], v144 offset:4640
	ds_read_b128 v[136:139], v144 offset:64
	ds_read_b128 v[140:143], v144 offset:4672
	s_waitcnt lgkmcnt(5)
	v_mfma_f32_32x32x16_bf16 v[98:113], v[224:227], v[146:149], 0
	ds_read_b128 v[224:227], v144 offset:96
	s_waitcnt lgkmcnt(5)
	v_mfma_f32_32x32x16_bf16 v[82:97], v[228:231], v[146:149], 0
	ds_read_b128 v[228:231], v144 offset:4704
	s_waitcnt lgkmcnt(5)
	v_mfma_f32_32x32x16_bf16 v[98:113], v[232:235], v[150:153], v[98:113]
	s_waitcnt lgkmcnt(4)
	v_mfma_f32_32x32x16_bf16 v[82:97], v[132:135], v[150:153], v[82:97]
	s_waitcnt lgkmcnt(3)
	v_mfma_f32_32x32x16_bf16 v[98:113], v[136:139], v[154:157], v[98:113]
	s_waitcnt lgkmcnt(2)
	v_mfma_f32_32x32x16_bf16 v[82:97], v[140:143], v[154:157], v[82:97]
	s_waitcnt lgkmcnt(1)
	v_mfma_f32_32x32x16_bf16 v[98:113], v[224:227], v[158:161], v[98:113]
	s_waitcnt lgkmcnt(0)
	v_mfma_f32_32x32x16_bf16 v[82:97], v[228:231], v[158:161], v[82:97]
.Lns_p2:
	s_cmp_lt_u32 s2, 2
	s_cbranch_scc1 .Lns_p3
	s_waitcnt vmcnt(0)

; template <int DV, bool HAS_V>
; DI void kv_sstore(const KVStage<DV>& st, unsigned char* buf) {
;     const int tid = threadIdx.x;
;     *(u32x4*)(buf + (tid >> 3) * KP + (tid & 7) * 16) = st.k[0];
;     if (HAS_V) {
; #pragma unroll
;         for (int i = 0; i < DV / 64; ++i) {
;             const int c = tid + 512 * i, kc = c & 7; unsigned char* q = buf + KT_BYTES + (c >> 3) * VP + (kc >> 1) * 32 + (kc & 1) * 8;
;             u32x2 lo, hi; lo.x = st.v[i].x; lo.y = st.v[i].y; hi.x = st.v[i].z; hi.y = st.v[i].w;
;             *(u32x2*)q = lo; *(u32x2*)(q + 16) = hi;
;         }
;     }
; }
	v_add_u32_e32 v236, s19, v194
	v_add_u32_e32 v237, v236, v195
	v_add3_u32 v236, v236, v196, v197
	v_add_u32_e32 v236, 0x2000, v236
	ds_write_b128 v237, v[114:117]
	ds_write2_b64 v236, v[118:119], v[120:121] offset0:128 offset1:130

;     ...
;     for (int i = 0; i < nt; ++i) {
;         const int j = jn;
;         const bool more = (i + 1 < nt);
;         if (more) { jn = next(j); if (probe != 1) kv_gload<DV, HAS_V>(st, Kb, VTb, ldv, jn * 64); }
	s_cmp_lt_u32 s2, 3
	s_cbranch_scc1 .Lns_p3

;     ...
;         kv_loop<64, true>(lds, Ks, VsT, 4096, nts, j0, [U](int j) { return __ffsll((long long)(U & (~0ull << (j + 1)))) - 1; }, [&](int j, const unsigned char* sb) {
	s_add_i32 s22, s8, 1
	s_lshl_b64 s[22:23], -1, s22
	s_and_b64 s[22:23], s[22:23], s[6:7]
	s_ff1_i32_b64 s9, s[22:23]

; template <int DV, bool HAS_V>
; DI void kv_gload(KVStage<DV>& st, const bf16_t* __restrict__ Kb, const bf16_t* __restrict__ VTb, int ldv, int key0) {
;     const int tid = threadIdx.x;
;     st.k[0] = *(const u32x4*)(Kb + (size_t)(key0 + (tid >> 3)) * 64 + (tid & 7) * 8);
;     if (HAS_V) {
; #pragma unroll
;         for (int i = 0; i < DV / 64; ++i) { const int c = tid + 512 * i; st.v[i] = *(const u32x4*)(VTb + (size_t)(key0 >> 6) * (DV * 64) + c * 8); }
;     }
; }
	s_waitcnt lgkmcnt(0)
	s_lshl_b32 s24, s9, 6
	v_add_u32_e32 v188, s24, v187
	v_mov_b32_e32 v189, v173
	v_lshlrev_b64 v[188:189], 7, v[188:189]
	v_lshl_add_u64 v[188:189], v[126:127], 0, v[188:189]
	global_load_dwordx4 v[114:117], v[188:189], off
	s_lshl_b32 s24, s9, 13
	s_mov_b32 s25, 0
	v_lshl_add_u64 v[190:191], v[128:129], 0, s[24:25]
	global_load_dwordx4 v[118:121], v[190:191], off

;     ...
;     for (int i = 0; i < nt; ++i) {
;         const int j = jn;
;         const bool more = (i + 1 < nt);
;         if (more) { jn = next(j); if (probe != 1) kv_gload<DV, HAS_V>(st, Kb, VTb, ldv, jn * 64); }
	s_cmp_lt_u32 s2, 4
	s_cbranch_scc1 .Lns_p3

;     ...
;         kv_loop<64, true>(lds, Ks, VsT, 4096, nts, j0, [U](int j) { return __ffsll((long long)(U & (~0ull << (j + 1)))) - 1; }, [&](int j, const unsigned char* sb) {
	s_add_i32 s22, s9, 1
	s_lshl_b64 s[22:23], -1, s22
	s_and_b64 s[22:23], s[22:23], s[6:7]
	s_ff1_i32_b64 s10, s[22:23]

; DI int crow(int i, int h) { return (i & 3) + 8 * (i >> 2) + 4 * h; }
; #define NEG_INF (-__builtin_inff())
;     ...
;             const bool mine = (mysel >> j) & 1ull;
;             if (__ballot(mine) != 0ull) {
;                 f32x16 s0, s1; attn_scores(sb, qf, r, h, s0, s1);
;                 if (j == (qb >> 6)) {
;                     const int lim = mine ? (qpos - 64 * j) : -1;
; #pragma unroll
;                     for (int i = 0; i < 16; ++i) {
;                         const int kl = crow(i, h);
;                         if (kl > lim) s0[i] = NEG_INF;
;                         if (kl + 32 > lim) s1[i] = NEG_INF;
.Lns_p3:
	s_waitcnt lgkmcnt(0)
	s_cmp_eq_u32 s28, 0
	s_cbranch_scc1 .Lns_loop
	s_barrier
.Lns_loop:
	s_cmp_eq_u64 s[14:15], 0
	s_cbranch_scc1 .Lns_xdone
	s_nop 3
	s_cmp_lg_u32 s12, s21
	s_cbranch_scc1 .Lns_nomask
	v_cndmask_b32_e64 v168, -1, v206, s[14:15]
	v_sub_u32_e32 v168, v168, v181

; DI int crow(int i, int h) { return (i & 3) + 8 * (i >> 2) + 4 * h; }
; DI float fast_exp2(float x) { return __builtin_amdgcn_exp2f(x); }
; DI float xhalf_max(float x) { auto rr = __builtin_amdgcn_permlane32_swap(__float_as_uint(x), __float_as_uint(x), false, false); return fmaxf(__uint_as_float(rr[0]), __uint_as_float(rr[1])); }
; #define NEG_INF (-__builtin_inff())
; template <int DV>
; DI void attn_softmax_pv(f32x16& s0, f32x16& s1, float& m, f32x16& lv, f32x16 (&o)[DV / 32], const unsigned char* vb, int r, int h, bool on = true) {
;     s0 = s0 * SM_C; s1 = s1 * SM_C;
;     const f32x16 t = __builtin_elementwise_max(s0, s1);
;     float mx = fmaxf(fmaxf(fmaxf(t[0], t[1]), fmaxf(t[2], t[3])), fmaxf(fmaxf(t[4], t[5]), fmaxf(t[6], t[7])));
;     mx = fmaxf(mx, fmaxf(fmaxf(fmaxf(t[8], t[9]), fmaxf(t[10], t[11])), fmaxf(fmaxf(t[12], t[13]), fmaxf(t[14], t[15]))));
;     mx = on ? mx : NEG_INF;
;     mx = xhalf_max(mx);
;     if (!__all(mx - m <= SM_THR)) {
;         const float mn = fmaxf(m, mx);
;         const float alpha = fast_exp2(m - mn);
;         lv = lv * alpha; m = mn;
; #pragma unroll
;         for (int dt = 0; dt < DV / 32; ++dt) o[dt] = o[dt] * alpha;
;     }
;     ...
;                     const int lim = mine ? (qpos - 64 * j) : -1;
; #pragma unroll
;                     for (int i = 0; i < 16; ++i) {
;                         const int kl = crow(i, h);
;                         if (kl > lim) s0[i] = NEG_INF;
;                         if (kl + 32 > lim) s1[i] = NEG_INF;
;                     }
	v_cmp_le_i32_e32 vcc, 0, v168
	s_nop 1
	v_cndmask_b32_e32 v98, v200, v98, vcc
	v_cmp_le_i32_e32 vcc, 32, v168
	s_nop 1
	v_cndmask_b32_e32 v82, v200, v82, vcc
	v_cmp_le_i32_e32 vcc, 1, v168
	s_nop 1
	v_cndmask_b32_e32 v99, v200, v99, vcc
	v_cmp_le_i32_e32 vcc, 33, v168
	s_nop 1
	v_cndmask_b32_e32 v83, v200, v83, vcc
	v_cmp_le_i32_e32 vcc, 2, v168
	s_nop 1
	v_cndmask_b32_e32 v100, v200, v100, vcc
	v_cmp_le_i32_e32 vcc, 34, v168
	s_nop 1
	v_cndmask_b32_e32 v84, v200, v84, vcc
	v_cmp_le_i32_e32 vcc, 3, v168
	s_nop 1
	v_cndmask_b32_e32 v101, v200, v101, vcc
	v_cmp_le_i32_e32 vcc, 35, v168
	s_nop 1
	v_cndmask_b32_e32 v85, v200, v85, vcc
	v_cmp_le_i32_e32 vcc, 8, v168
	s_nop 1
	v_cndmask_b32_e32 v102, v200, v102, vcc
	v_cmp_le_i32_e32 vcc, 40, v168
	s_nop 1
	v_cndmask_b32_e32 v86, v200, v86, vcc
	v_cmp_le_i32_e32 vcc, 9, v168
	s_nop 1
	v_cndmask_b32_e32 v103, v200, v103, vcc
	v_cmp_le_i32_e32 vcc, 41, v168
	s_nop 1
	v_cndmask_b32_e32 v87, v200, v87, vcc
	v_cmp_le_i32_e32 vcc, 10, v168
	s_nop 1
	v_cndmask_b32_e32 v104, v200, v104, vcc
	v_cmp_le_i32_e32 vcc, 42, v168
	s_nop 1
	v_cndmask_b32_e32 v88, v200, v88, vcc
	v_cmp_le_i32_e32 vcc, 11, v168
	s_nop 1
	v_cndmask_b32_e32 v105, v200, v105, vcc
	v_cmp_le_i32_e32 vcc, 43, v168
	s_nop 1
	v_cndmask_b32_e32 v89, v200, v89, vcc
	v_cmp_le_i32_e32 vcc, 16, v168
	s_nop 1
	v_cndmask_b32_e32 v106, v200, v106, vcc
	v_cmp_le_i32_e32 vcc, 48, v168
	s_nop 1
	v_cndmask_b32_e32 v90, v200, v90, vcc
	v_cmp_le_i32_e32 vcc, 17, v168
	s_nop 1
	v_cndmask_b32_e32 v107, v200, v107, vcc
	v_cmp_le_i32_e32 vcc, 49, v168
	s_nop 1
	v_cndmask_b32_e32 v91, v200, v91, vcc
	v_cmp_le_i32_e32 vcc, 18, v168
	s_nop 1
	v_cndmask_b32_e32 v108, v200, v108, vcc
	v_cmp_le_i32_e32 vcc, 50, v168
	s_nop 1
	v_cndmask_b32_e32 v92, v200, v92, vcc
	v_cmp_le_i32_e32 vcc, 19, v168
	s_nop 1
	v_cndmask_b32_e32 v109, v200, v109, vcc
	v_cmp_le_i32_e32 vcc, 51, v168
	s_nop 1
	v_cndmask_b32_e32 v93, v200, v93, vcc
	v_cmp_le_i32_e32 vcc, 24, v168
	s_nop 1
	v_cndmask_b32_e32 v110, v200, v110, vcc
	v_cmp_le_i32_e32 vcc, 56, v168
	s_nop 1
	v_cndmask_b32_e32 v94, v200, v94, vcc
	v_cmp_le_i32_e32 vcc, 25, v168
	s_nop 1
	v_cndmask_b32_e32 v111, v200, v111, vcc
	v_cmp_le_i32_e32 vcc, 57, v168
	s_nop 1
	v_cndmask_b32_e32 v95, v200, v95, vcc
	v_cmp_le_i32_e32 vcc, 26, v168
	s_nop 1
	v_cndmask_b32_e32 v112, v200, v112, vcc
	v_cmp_le_i32_e32 vcc, 58, v168
	s_nop 1
	v_cndmask_b32_e32 v96, v200, v96, vcc
	v_cmp_le_i32_e32 vcc, 27, v168
	s_nop 1
	v_cndmask_b32_e32 v113, v200, v113, vcc
	v_cmp_le_i32_e32 vcc, 59, v168
	s_nop 1
	v_cndmask_b32_e32 v97, v200, v97, vcc
.Lns_nomask:
	v_max3_f32 v162, v98, v99, v100
	v_max3_f32 v163, v101, v102, v103
	v_max3_f32 v164, v104, v105, v106
	v_max3_f32 v165, v107, v108, v109
	v_max3_f32 v166, v110, v111, v112
	v_max3_f32 v162, v162, v113, v82
	v_max3_f32 v163, v163, v83, v84
	v_max3_f32 v164, v164, v85, v86
	v_max3_f32 v165, v165, v87, v88
	v_max3_f32 v166, v166, v89, v90
	v_max3_f32 v162, v162, v91, v92
	v_max3_f32 v163, v163, v93, v94
	v_max3_f32 v164, v164, v95, v96
	v_max3_f32 v162, v162, v97, v163
	v_max3_f32 v162, v162, v164, v165
	v_max_f32_e32 v162, v162, v166
	v_mul_f32_e32 v162, s70, v162
	v_cndmask_b32_e64 v162, v200, v162, s[14:15]
	v_mov_b32_e32 v163, v162
	s_nop 1
	v_permlane32_swap_b32_e32 v162, v163
	v_max_f32_e32 v162, v162, v163
	v_sub_f32_e32 v163, v162, v207
	v_cmp_ge_f32_e32 vcc, s78, v163
	s_cmp_eq_u64 vcc, exec
	s_cbranch_scc1 .Lns_nr
	v_max_f32_e32 v163, v207, v162
	v_sub_f32_e32 v162, v207, v163
	v_exp_f32_e32 v162, v162
	v_mov_b32_e32 v207, v163
	s_nop 0
	v_pk_mul_f32 v[80:81], v[80:81], v[162:163] op_sel_hi:[1,0]
	v_pk_mul_f32 v[78:79], v[78:79], v[162:163] op_sel_hi:[1,0]
	v_pk_mul_f32 v[76:77], v[76:77], v[162:163] op_sel_hi:[1,0]
	v_pk_mul_f32 v[74:75], v[74:75], v[162:163] op_sel_hi:[1,0]
	v_pk_mul_f32 v[72:73], v[72:73], v[162:163] op_sel_hi:[1,0]
	v_pk_mul_f32 v[70:71], v[70:71], v[162:163] op_sel_hi:[1,0]
	v_pk_mul_f32 v[68:69], v[68:69], v[162:163] op_sel_hi:[1,0]
	v_pk_mul_f32 v[66:67], v[66:67], v[162:163] op_sel_hi:[1,0]
	v_pk_mul_f32 v[64:65], v[64:65], v[162:163] op_sel_hi:[1,0]
	v_pk_mul_f32 v[62:63], v[62:63], v[162:163] op_sel_hi:[1,0]
	v_pk_mul_f32 v[60:61], v[60:61], v[162:163] op_sel_hi:[1,0]
	v_pk_mul_f32 v[58:59], v[58:59], v[162:163] op_sel_hi:[1,0]
	v_pk_mul_f32 v[56:57], v[56:57], v[162:163] op_sel_hi:[1,0]
	v_pk_mul_f32 v[54:55], v[54:55], v[162:163] op_sel_hi:[1,0]
	v_pk_mul_f32 v[52:53], v[52:53], v[162:163] op_sel_hi:[1,0]
	v_pk_mul_f32 v[50:51], v[50:51], v[162:163] op_sel_hi:[1,0]
	v_pk_mul_f32 v[48:49], v[48:49], v[162:163] op_sel_hi:[1,0]
	v_pk_mul_f32 v[46:47], v[46:47], v[162:163] op_sel_hi:[1,0]
	v_pk_mul_f32 v[44:45], v[44:45], v[162:163] op_sel_hi:[1,0]
	v_pk_mul_f32 v[42:43], v[42:43], v[162:163] op_sel_hi:[1,0]
	v_pk_mul_f32 v[40:41], v[40:41], v[162:163] op_sel_hi:[1,0]
	v_pk_mul_f32 v[38:39], v[38:39], v[162:163] op_sel_hi:[1,0]
	v_pk_mul_f32 v[36:37], v[36:37], v[162:163] op_sel_hi:[1,0]
	v_pk_mul_f32 v[34:35], v[34:35], v[162:163] op_sel_hi:[1,0]
; DI unsigned pk_bf16(float a, float b) { f32x2 v = {a, b}; return __builtin_bit_cast(unsigned, __builtin_convertvector(v, bf16v2)); }
; DI float fast_exp2(float x) { return __builtin_amdgcn_exp2f(x); }
; DI void pack_p(const f32x16& p0, const f32x16& p1, bf16x8 (&pf)[2][2]) {
; #pragma unroll
;     for (int sp = 0; sp < 2; ++sp) {
;         u32x4 a, b;
;         a.x = pk_bf16(p0[8 * sp + 0], p0[8 * sp + 1]); a.y = pk_bf16(p0[8 * sp + 2], p0[8 * sp + 3]);
;         a.z = pk_bf16(p0[8 * sp + 4], p0[8 * sp + 5]); a.w = pk_bf16(p0[8 * sp + 6], p0[8 * sp + 7]);
;         b.x = pk_bf16(p1[8 * sp + 0], p1[8 * sp + 1]); b.y = pk_bf16(p1[8 * sp + 2], p1[8 * sp + 3]);
;         b.z = pk_bf16(p1[8 * sp + 4], p1[8 * sp + 5]); b.w = pk_bf16(p1[8 * sp + 6], p1[8 * sp + 7]);
;         pf[0][sp] = __builtin_bit_cast(bf16x8, a); pf[1][sp] = __builtin_bit_cast(bf16x8, b);
;     }
; }
; template <int DV>
; DI void attn_softmax_pv(f32x16& s0, f32x16& s1, float& m, f32x16& lv, f32x16 (&o)[DV / 32], const unsigned char* vb, int r, int h, bool on = true) {
;     ...
;     const float msub = on ? m : __builtin_inff();
;     s0 = s0 - msub; s1 = s1 - msub;
; #pragma unroll
;     for (int i = 0; i < 16; ++i) { s0[i] = fast_exp2(s0[i]); s1[i] = fast_exp2(s1[i]); }
;     lv = lv + (s0 + s1);
;     bf16x8 pf[2][2]; pack_p(s0, s1, pf);
.Lns_nr:
	v_cndmask_b32_e64 v167, v201, v207, s[14:15]
	v_fma_f32 v98, v98, s70, -v167
	v_fma_f32 v99, v99, s70, -v167
	v_fma_f32 v100, v100, s70, -v167
	v_fma_f32 v101, v101, s70, -v167
	v_fma_f32 v102, v102, s70, -v167
	v_fma_f32 v103, v103, s70, -v167
	v_fma_f32 v104, v104, s70, -v167
	v_fma_f32 v105, v105, s70, -v167
	v_exp_f32_e32 v98, v98
	v_exp_f32_e32 v99, v99
	v_exp_f32_e32 v100, v100
	v_exp_f32_e32 v101, v101
	v_exp_f32_e32 v102, v102
	v_exp_f32_e32 v103, v103
	v_exp_f32_e32 v104, v104
	v_exp_f32_e32 v105, v105
	v_fma_f32 v106, v106, s70, -v167
	v_fma_f32 v107, v107, s70, -v167
	v_fma_f32 v108, v108, s70, -v167
	v_fma_f32 v109, v109, s70, -v167
	v_fma_f32 v110, v110, s70, -v167
	v_fma_f32 v111, v111, s70, -v167
	v_fma_f32 v112, v112, s70, -v167
	v_fma_f32 v113, v113, s70, -v167
	v_exp_f32_e32 v106, v106
	v_exp_f32_e32 v107, v107
	v_exp_f32_e32 v108, v108
	v_exp_f32_e32 v109, v109
	v_exp_f32_e32 v110, v110
	v_exp_f32_e32 v111, v111
	v_exp_f32_e32 v112, v112
	v_exp_f32_e32 v113, v113
	v_fma_f32 v82, v82, s70, -v167
	v_fma_f32 v83, v83, s70, -v167
	v_fma_f32 v84, v84, s70, -v167
	v_fma_f32 v85, v85, s70, -v167
	v_fma_f32 v86, v86, s70, -v167
	v_fma_f32 v87, v87, s70, -v167
	v_fma_f32 v88, v88, s70, -v167
	v_fma_f32 v89, v89, s70, -v167
	v_exp_f32_e32 v82, v82
	v_exp_f32_e32 v83, v83
	v_exp_f32_e32 v84, v84
	v_exp_f32_e32 v85, v85
	v_exp_f32_e32 v86, v86
	v_exp_f32_e32 v87, v87
	v_exp_f32_e32 v88, v88
	v_exp_f32_e32 v89, v89
	v_fma_f32 v90, v90, s70, -v167
	v_fma_f32 v91, v91, s70, -v167
	v_fma_f32 v92, v92, s70, -v167
	v_fma_f32 v93, v93, s70, -v167
	v_fma_f32 v94, v94, s70, -v167
	v_fma_f32 v95, v95, s70, -v167
	v_fma_f32 v96, v96, s70, -v167
	v_fma_f32 v97, v97, s70, -v167
	v_exp_f32_e32 v90, v90
	v_exp_f32_e32 v91, v91
	v_exp_f32_e32 v92, v92
	v_exp_f32_e32 v93, v93
	v_exp_f32_e32 v94, v94
	v_exp_f32_e32 v95, v95
	v_exp_f32_e32 v96, v96
	v_exp_f32_e32 v97, v97
	v_cvt_pk_bf16_f32 v208, v98, v99
	v_cvt_pk_bf16_f32 v209, v100, v101
	v_cvt_pk_bf16_f32 v210, v102, v103
	v_cvt_pk_bf16_f32 v211, v104, v105
	v_cvt_pk_bf16_f32 v212, v106, v107
	v_cvt_pk_bf16_f32 v213, v108, v109
	v_cvt_pk_bf16_f32 v214, v110, v111
	v_cvt_pk_bf16_f32 v215, v112, v113
	v_cvt_pk_bf16_f32 v216, v82, v83
	v_cvt_pk_bf16_f32 v217, v84, v85
	v_cvt_pk_bf16_f32 v218, v86, v87
	v_cvt_pk_bf16_f32 v219, v88, v89
	v_cvt_pk_bf16_f32 v220, v90, v91
	v_cvt_pk_bf16_f32 v221, v92, v93
	v_cvt_pk_bf16_f32 v222, v94, v95
	v_cvt_pk_bf16_f32 v223, v96, v97
	v_add_f32_e32 v98, v98, v82
	v_add_f32_e32 v99, v99, v83
	v_add_f32_e32 v66, v66, v98
	v_add_f32_e32 v100, v100, v84
	v_add_f32_e32 v67, v67, v99
	v_add_f32_e32 v101, v101, v85
	v_add_f32_e32 v68, v68, v100
	v_add_f32_e32 v102, v102, v86
	v_add_f32_e32 v69, v69, v101
	v_add_f32_e32 v103, v103, v87
	v_add_f32_e32 v70, v70, v102
	v_add_f32_e32 v104, v104, v88
	v_add_f32_e32 v71, v71, v103
	v_add_f32_e32 v105, v105, v89
	v_add_f32_e32 v72, v72, v104
	v_add_f32_e32 v106, v106, v90
	v_add_f32_e32 v73, v73, v105
	v_add_f32_e32 v107, v107, v91
	v_add_f32_e32 v74, v74, v106
	v_add_f32_e32 v108, v108, v92
	v_add_f32_e32 v75, v75, v107
	v_add_f32_e32 v109, v109, v93
	v_add_f32_e32 v76, v76, v108
	v_add_f32_e32 v110, v110, v94
	v_add_f32_e32 v77, v77, v109
	v_add_f32_e32 v111, v111, v95
	v_add_f32_e32 v78, v78, v110
	v_add_f32_e32 v112, v112, v96
	v_add_f32_e32 v79, v79, v111
	v_add_f32_e32 v113, v113, v97
	v_add_f32_e32 v80, v80, v112
	v_add_f32_e32 v81, v81, v113
.Lns_xdone:
	s_waitcnt lgkmcnt(0)
	s_barrier
	s_add_i32 s26, s13, 1
	s_mov_b64 s[16:17], 0
	s_cmp_ge_u32 s26, s2
	s_cbranch_scc1 .Lns_y1

;     ...
;             const bool mine = (mysel >> j) & 1ull;
	v_lshrrev_b64 v[168:169], s8, v[124:125]
	v_and_b32_e32 v168, 1, v168
	v_cmp_ne_u32_e64 s[16:17], 0, v168

;     ...
;             const bool mine = (mysel >> j) & 1ull;
;             if (__ballot(mine) != 0ull) {
;                 f32x16 s0, s1; attn_scores(sb, qf, r, h, s0, s1);
.Lns_y1:
	v_add3_u32 v145, s18, v204, v180
	v_add3_u32 v144, s19, v204, v180
	s_cmp_eq_u64 s[14:15], 0
	s_cbranch_scc1 .Lns_noa
	s_cmp_eq_u64 s[16:17], 0
	s_cbranch_scc1 .Lns_pvonly

; #define MFMA(a, b, c) __builtin_amdgcn_mfma_f32_32x32x16_bf16((a), (b), (c), 0, 0, 0)
; DI void attn_scores(const unsigned char* kb, const bf16x8 (&qf)[4], int r, int h, f32x16& s0, f32x16& s1) {
; #pragma unroll
;     for (int i = 0; i < 16; ++i) { s0[i] = 0.f; s1[i] = 0.f; }
; #pragma unroll
;     for (int s = 0; s < 4; ++s) {
;         const bf16x8 k0 = *(const bf16x8*)(kb + r * KP + s * 32 + h * 16);
;         const bf16x8 k1 = *(const bf16x8*)(kb + (32 + r) * KP + s * 32 + h * 16);
;         s0 = MFMA(k0, qf[s], s0); s1 = MFMA(k1, qf[s], s1);
;     }
; }
; template <int DV>
; DI void attn_pv(const unsigned char* vb, const bf16x8 (&pf)[2][2], int r, int h, f32x16 (&o)[DV / 32]) {
; #pragma unroll
;     for (int dt = 0; dt < DV / 32; ++dt)
; #pragma unroll
;         for (int mt = 0; mt < 2; ++mt)
; #pragma unroll
;             for (int sp = 0; sp < 2; ++sp) {
;                 const bf16x8 vf = *(const bf16x8*)(vb + (dt * 32 + r) * VP + (2 * mt + sp) * 32 + h * 16);
;                 o[dt] = MFMA(vf, pf[mt][sp], o[dt]);
;             }
; }
	ds_read_b128 v[224:227], v145 offset:9216
	ds_read_b128 v[228:231], v145 offset:9248
	ds_read_b128 v[232:235], v145 offset:9280
	ds_read_b128 v[132:135], v145 offset:9312
	ds_read_b128 v[136:139], v145 offset:13824
	ds_read_b128 v[140:143], v145 offset:13856
	s_waitcnt lgkmcnt(5)
	v_mfma_f32_32x32x16_bf16 v[50:65], v[224:227], v[208:211], v[50:65]
	ds_read_b128 v[224:227], v145 offset:13888
	s_waitcnt lgkmcnt(5)
	v_mfma_f32_32x32x16_bf16 v[50:65], v[228:231], v[212:215], v[50:65]
	ds_read_b128 v[228:231], v145 offset:13920
	s_waitcnt lgkmcnt(5)
	v_mfma_f32_32x32x16_bf16 v[50:65], v[232:235], v[216:219], v[50:65]
	ds_read_b128 v[232:235], v144 offset:0
	s_waitcnt lgkmcnt(5)
	v_mfma_f32_32x32x16_bf16 v[50:65], v[132:135], v[220:223], v[50:65]
	ds_read_b128 v[132:135], v144 offset:4608
	s_waitcnt lgkmcnt(5)
	v_mfma_f32_32x32x16_bf16 v[34:49], v[136:139], v[208:211], v[34:49]
	ds_read_b128 v[136:139], v144 offset:32
	s_waitcnt lgkmcnt(5)
	v_mfma_f32_32x32x16_bf16 v[34:49], v[140:143], v[212:215], v[34:49]
	ds_read_b128 v[140:143], v144 offset:4640
	s_waitcnt lgkmcnt(5)
	v_mfma_f32_32x32x16_bf16 v[34:49], v[224:227], v[216:219], v[34:49]
	ds_read_b128 v[224:227], v144 offset:64
	s_waitcnt lgkmcnt(5)
	v_mfma_f32_32x32x16_bf16 v[34:49], v[228:231], v[220:223], v[34:49]
	ds_read_b128 v[228:231], v144 offset:4672
	s_waitcnt lgkmcnt(5)
	v_mfma_f32_32x32x16_bf16 v[98:113], v[232:235], v[146:149], 0
	ds_read_b128 v[232:235], v144 offset:96
	s_waitcnt lgkmcnt(5)
	v_mfma_f32_32x32x16_bf16 v[82:97], v[132:135], v[146:149], 0
	ds_read_b128 v[132:135], v144 offset:4704
	s_waitcnt lgkmcnt(5)
	v_mfma_f32_32x32x16_bf16 v[98:113], v[136:139], v[150:153], v[98:113]
	s_waitcnt lgkmcnt(4)
	v_mfma_f32_32x32x16_bf16 v[82:97], v[140:143], v[150:153], v[82:97]
	s_waitcnt lgkmcnt(3)
	v_mfma_f32_32x32x16_bf16 v[98:113], v[224:227], v[154:157], v[98:113]
	s_waitcnt lgkmcnt(2)
	v_mfma_f32_32x32x16_bf16 v[82:97], v[228:231], v[154:157], v[82:97]
	s_waitcnt lgkmcnt(1)
	v_mfma_f32_32x32x16_bf16 v[98:113], v[232:235], v[158:161], v[98:113]
	s_waitcnt lgkmcnt(0)
	v_mfma_f32_32x32x16_bf16 v[82:97], v[132:135], v[158:161], v[82:97]
	s_branch .Lns_stage
.Lns_pvonly:
	ds_read_b128 v[224:227], v145 offset:9216
	ds_read_b128 v[228:231], v145 offset:9248
	ds_read_b128 v[232:235], v145 offset:9280
	ds_read_b128 v[132:135], v145 offset:9312
	ds_read_b128 v[136:139], v145 offset:13824
	ds_read_b128 v[140:143], v145 offset:13856
	s_waitcnt lgkmcnt(5)
	v_mfma_f32_32x32x16_bf16 v[50:65], v[224:227], v[208:211], v[50:65]
	ds_read_b128 v[224:227], v145 offset:13888
	s_waitcnt lgkmcnt(5)
	v_mfma_f32_32x32x16_bf16 v[50:65], v[228:231], v[212:215], v[50:65]
	ds_read_b128 v[228:231], v145 offset:13920
	s_waitcnt lgkmcnt(5)
	v_mfma_f32_32x32x16_bf16 v[50:65], v[232:235], v[216:219], v[50:65]
	s_waitcnt lgkmcnt(4)
	v_mfma_f32_32x32x16_bf16 v[50:65], v[132:135], v[220:223], v[50:65]
	s_waitcnt lgkmcnt(3)
	v_mfma_f32_32x32x16_bf16 v[34:49], v[136:139], v[208:211], v[34:49]
	s_waitcnt lgkmcnt(2)
	v_mfma_f32_32x32x16_bf16 v[34:49], v[140:143], v[212:215], v[34:49]
	s_waitcnt lgkmcnt(1)
	v_mfma_f32_32x32x16_bf16 v[34:49], v[224:227], v[216:219], v[34:49]
	s_waitcnt lgkmcnt(0)
	v_mfma_f32_32x32x16_bf16 v[34:49], v[228:231], v[220:223], v[34:49]
	s_branch .Lns_stage
.Lns_noa:
	s_cmp_eq_u64 s[16:17], 0
	s_cbranch_scc1 .Lns_stage
	ds_read_b128 v[224:227], v144 offset:0
	ds_read_b128 v[228:231], v144 offset:4608
	ds_read_b128 v[232:235], v144 offset:32
	ds_read_b128 v[132:135], v144 offset:4640
	ds_read_b128 v[136:139], v144 offset:64
	ds_read_b128 v[140:143], v144 offset:4672
	s_waitcnt lgkmcnt(5)
	v_mfma_f32_32x32x16_bf16 v[98:113], v[224:227], v[146:149], 0
	ds_read_b128 v[224:227], v144 offset:96
	s_waitcnt lgkmcnt(5)
	v_mfma_f32_32x32x16_bf16 v[82:97], v[228:231], v[146:149], 0
	ds_read_b128 v[228:231], v144 offset:4704
	s_waitcnt lgkmcnt(5)
	v_mfma_f32_32x32x16_bf16 v[98:113], v[232:235], v[150:153], v[98:113]
	s_waitcnt lgkmcnt(4)
	v_mfma_f32_32x32x16_bf16 v[82:97], v[132:135], v[150:153], v[82:97]
	s_waitcnt lgkmcnt(3)
	v_mfma_f32_32x32x16_bf16 v[98:113], v[136:139], v[154:157], v[98:113]
	s_waitcnt lgkmcnt(2)
	v_mfma_f32_32x32x16_bf16 v[82:97], v[140:143], v[154:157], v[82:97]
	s_waitcnt lgkmcnt(1)
	v_mfma_f32_32x32x16_bf16 v[98:113], v[224:227], v[158:161], v[98:113]
	s_waitcnt lgkmcnt(0)
	v_mfma_f32_32x32x16_bf16 v[82:97], v[228:231], v[158:161], v[82:97]
.Lns_stage:
	s_mov_b32 s27, s10
	s_add_i32 s26, s13, 2
	s_cmp_ge_u32 s26, s2
	s_cbranch_scc1 .Lns_next
	s_waitcnt vmcnt(0)

; template <int DV, bool HAS_V>
; DI void kv_sstore(const KVStage<DV>& st, unsigned char* buf) {
;     const int tid = threadIdx.x;
;     *(u32x4*)(buf + (tid >> 3) * KP + (tid & 7) * 16) = st.k[0];
;     if (HAS_V) {
; #pragma unroll
;         for (int i = 0; i < DV / 64; ++i) {
;             const int c = tid + 512 * i, kc = c & 7; unsigned char* q = buf + KT_BYTES + (c >> 3) * VP + (kc >> 1) * 32 + (kc & 1) * 8;
;             u32x2 lo, hi; lo.x = st.v[i].x; lo.y = st.v[i].y; hi.x = st.v[i].z; hi.y = st.v[i].w;
;             *(u32x2*)q = lo; *(u32x2*)(q + 16) = hi;
;         }
;     }
; }
	v_add_u32_e32 v236, s20, v194
	v_add_u32_e32 v237, v236, v195
	v_add3_u32 v236, v236, v196, v197
	v_add_u32_e32 v236, 0x2000, v236
	ds_write_b128 v237, v[114:117]
	ds_write2_b64 v236, v[118:119], v[120:121] offset0:128 offset1:130

;     ...
;     for (int i = 0; i < nt; ++i) {
;         const int j = jn;
;         const bool more = (i + 1 < nt);
;         if (more) { jn = next(j); if (probe != 1) kv_gload<DV, HAS_V>(st, Kb, VTb, ldv, jn * 64); }
;         if (probe != 2) body(j, (const unsigned char*)(lds + (i & 1) * SB));
;         if (more && probe != 1) kv_sstore<DV, HAS_V>(st, lds + ((i + 1) & 1) * SB);
	s_add_i32 s26, s13, 3
	s_cmp_ge_u32 s26, s2
	s_cbranch_scc1 .Lns_next
	s_waitcnt lgkmcnt(0)

; template <int DV, bool HAS_V>
; DI void kv_gload(KVStage<DV>& st, const bf16_t* __restrict__ Kb, const bf16_t* __restrict__ VTb, int ldv, int key0) {
;     const int tid = threadIdx.x;
;     st.k[0] = *(const u32x4*)(Kb + (size_t)(key0 + (tid >> 3)) * 64 + (tid & 7) * 8);
;     if (HAS_V) {
; #pragma unroll
;         for (int i = 0; i < DV / 64; ++i) { const int c = tid + 512 * i; st.v[i] = *(const u32x4*)(VTb + (size_t)(key0 >> 6) * (DV * 64) + c * 8); }
;     }
; }
	s_lshl_b32 s24, s10, 6
	v_add_u32_e32 v188, s24, v187
	v_mov_b32_e32 v189, v173
	v_lshlrev_b64 v[188:189], 7, v[188:189]
	v_lshl_add_u64 v[188:189], v[126:127], 0, v[188:189]
	global_load_dwordx4 v[114:117], v[188:189], off
	s_lshl_b32 s24, s10, 13
	s_mov_b32 s25, 0
	v_lshl_add_u64 v[190:191], v[128:129], 0, s[24:25]
	global_load_dwordx4 v[118:121], v[190:191], off

;     ...
;     for (int i = 0; i < nt; ++i) {
;         const int j = jn;
;         const bool more = (i + 1 < nt);
;         if (more) { jn = next(j); if (probe != 1) kv_gload<DV, HAS_V>(st, Kb, VTb, ldv, jn * 64); }
	s_add_i32 s26, s13, 4
	s_cmp_ge_u32 s26, s2
	s_cbranch_scc1 .Lns_next

;     ...
;         kv_loop<64, true>(lds, Ks, VsT, 4096, nts, j0, [U](int j) { return __ffsll((long long)(U & (~0ull << (j + 1)))) - 1; }, [&](int j, const unsigned char* sb) {
	s_add_i32 s22, s10, 1
	s_lshl_b64 s[22:23], -1, s22
	s_and_b64 s[22:23], s[22:23], s[6:7]
	s_ff1_i32_b64 s27, s[22:23]

;     ...
;     for (int i = 0; i < nt; ++i) {
;         const int j = jn;
;         const bool more = (i + 1 < nt);
;         if (more) { jn = next(j); if (probe != 1) kv_gload<DV, HAS_V>(st, Kb, VTb, ldv, jn * 64); }
;         if (probe != 2) body(j, (const unsigned char*)(lds + (i & 1) * SB));
;         if (more && probe != 1) kv_sstore<DV, HAS_V>(st, lds + ((i + 1) & 1) * SB);
;         __syncthreads();
;     }
.Lns_next:
	s_mov_b32 s12, s8
	s_mov_b32 s8, s9
	s_mov_b32 s9, s10
	s_mov_b32 s10, s27
	s_mov_b64 s[14:15], s[16:17]
	s_mov_b32 s26, s18
	s_mov_b32 s18, s19
	s_mov_b32 s19, s20
	s_mov_b32 s20, s26
	s_add_i32 s13, s13, 1
	s_waitcnt lgkmcnt(0)
	s_barrier
	s_cmp_lt_u32 s13, s2
	s_cbranch_scc1 .Lns_loop
	s_cmp_lg_u32 s28, 0
	s_cbranch_scc1 .LBB0_557
	s_barrier
	s_branch .LBB0_557

